# w_in epilogue U/Q/K/V stores write-through sc1 (consumers sit on other XCDs)
# baseline (speedup 1.0000x reference)
; __device__ __forceinline__ unsigned cvt_pk_bf16(float lo, float hi) { unsigned r; asm volatile("v_cvt_pk_bf16_f32 %0, %1, %2" : "=v"(r) : "v"(lo), "v"(hi)); return r; }
;     __device__ __forceinline__ void operator()(const f32x4 (&acc)[2][2][4][2], const Unit& u, int wr, int wc, int fr, int fq, PG8_LAS float* xt) const {
;     ...
;                 for (int m = 0; m < 4; ++m) { const int row = row0 + ai * HALF + m * 16;
;                     const f32x4 cs = *(const f32x4*)(cosT + (size_t)row * 64 + d1), sn = *(const f32x4*)(sinT + (size_t)row * 64 + d1);
; #pragma unroll
;                     for (int bj = 0; bj < 2; ++bj) { const f32x4 x1 = acc[ai][bj][m][0], x2 = acc[ai][bj][m][1];
;                         float s = (x1[0] * x1[0] + x1[1] * x1[1]) + (x1[2] * x1[2] + x1[3] * x1[3]) + (x2[0] * x2[0] + x2[1] * x2[1]) + (x2[2] * x2[2] + x2[3] * x2[3]);
;                         s += __shfl_xor(s, 16); s += __shfl_xor(s, 32);
;                         const int hidx = (pn - 4) * 2 + bj;
;                         if (fq == 0) xt[((ai * HALF + wr * 64 + m * 16 + fr) * 2 + bj) * 4 + wc] = s;
;                         const f32x4 a1 = x1 * g1, a2 = x2 * g2;
;                         const f32x4 y1 = a1 * cs - a2 * sn, y2 = a2 * cs + a1 * sn;
;                         u32x2 w1; w1.x = cvt_pk_bf16(y1[0], y1[1]); w1.y = cvt_pk_bf16(y1[2], y1[3]);
;                         u32x2 w2; w2.x = cvt_pk_bf16(y2[0], y2[1]); w2.y = cvt_pk_bf16(y2[2], y2[3]);
;                         const bool odd = (fq & 1) != 0;
;                         const unsigned sx = odd ? w1.x : w2.x, sy = odd ? w1.y : w2.y;
;                         const unsigned rx = (unsigned)__shfl_xor((int)sx, 16), ry = (unsigned)__shfl_xor((int)sy, 16);
;                         u32x4 wv; if (odd) { wv.x = rx; wv.y = ry; wv.z = w2.x; wv.w = w2.y; } else { wv.x = w1.x; wv.y = w1.y; wv.z = rx; wv.w = ry; }
;                         bf16_t* p = O + (size_t)row * 1024 + (hidx & 7) * 128 + (odd ? (64 + d1 - 4) : d1);
;                         *(u32x4*)p = wv; } }
.LBB0_412:
	s_or_b64 exec, exec, s[16:17]
	s_waitcnt vmcnt(0)
	v_pk_mul_f32 v[178:179], v[124:125], v[132:133]
	v_pk_mul_f32 v[180:181], v[122:123], v[130:131]
	v_pk_mul_f32 v[166:167], v[128:129], v[136:137]
	v_pk_mul_f32 v[176:177], v[126:127], v[134:135]
	v_pk_mul_f32 v[182:183], v[178:179], v[144:145]
	v_pk_mul_f32 v[184:185], v[180:181], v[142:143]
	v_pk_fma_f32 v[182:183], v[166:167], v[140:141], v[182:183] neg_lo:[0,0,1] neg_hi:[0,0,1]
	v_pk_fma_f32 v[184:185], v[176:177], v[138:139], v[184:185] neg_lo:[0,0,1] neg_hi:[0,0,1]
	v_pk_mul_f32 v[166:167], v[166:167], v[144:145]
	v_pk_mul_f32 v[176:177], v[176:177], v[142:143]
	v_pk_fma_f32 v[166:167], v[140:141], v[178:179], v[166:167]
	v_pk_fma_f32 v[176:177], v[138:139], v[180:181], v[176:177]
	v_cvt_pk_bf16_f32 v175, v184, v185
	v_cvt_pk_bf16_f32 v178, v182, v183
	s_and_b64 s[6:7], s[14:15], exec
	v_cvt_pk_bf16_f32 v176, v176, v177
	v_cvt_pk_bf16_f32 v177, v166, v167
	s_mov_b32 s6, 0x19200000
	v_cndmask_b32_e64 v166, v178, v177, s[36:37]
	ds_bpermute_b32 v179, v218, v166
	v_cndmask_b32_e64 v180, v175, v176, s[36:37]
	ds_bpermute_b32 v182, v218, v180
	v_mul_f32_e32 v180, v121, v121
	v_fmac_f32_e32 v180, v120, v120
	s_waitcnt lgkmcnt(1)
	v_cndmask_b32_e64 v181, v177, v179, s[36:37]
	v_mul_f32_e32 v177, v119, v119
	v_fmac_f32_e32 v177, v118, v118
	v_add_f32_e32 v177, v177, v180
	v_mul_f32_e32 v180, v115, v115
	v_fmac_f32_e32 v180, v114, v114
	v_add_f32_e32 v177, v177, v180
	v_mul_f32_e32 v180, v117, v117
	v_fmac_f32_e32 v180, v116, v116
	v_add_f32_e32 v177, v180, v177
	ds_bpermute_b32 v183, v218, v177
	v_cndmask_b32_e64 v179, v179, v178, s[36:37]
	s_waitcnt lgkmcnt(1)
	v_cndmask_b32_e64 v178, v182, v175, s[36:37]
	v_cndmask_b32_e64 v180, v176, v182, s[36:37]
	s_cselect_b32 s76, s6, 0x1a200000
	s_waitcnt lgkmcnt(0)
	v_add_f32_e32 v175, v177, v183
	ds_bpermute_b32 v176, v219, v175
	s_lshl_b32 s6, s2, 8
	v_lshl_add_u64 v[164:165], v[152:153], 0, s[76:77]
	v_lshlrev_b64 v[166:167], 11, v[162:163]
	s_and_b32 s6, s6, 0x300
	v_lshl_add_u64 v[166:167], v[164:165], 0, v[166:167]
	s_lshl_b32 s76, s6, 1
	v_lshl_add_u64 v[166:167], v[166:167], 0, s[76:77]
	flat_store_dwordx4 v[166:167], v[178:181] sc1
	s_and_saveexec_b64 s[14:15], s[34:35]
	s_cbranch_execz .LBB0_414
	s_waitcnt lgkmcnt(0)
	v_add_f32_e32 v175, v175, v176
	ds_write_b32 v174, v175 offset:16
.LBB0_414:
	s_or_b64 exec, exec, s[14:15]
	s_waitcnt lgkmcnt(0)
	v_pk_mul_f32 v[176:177], v[120:121], v[136:137]
	v_pk_mul_f32 v[178:179], v[118:119], v[134:135]
	v_pk_mul_f32 v[180:181], v[116:117], v[132:133]
	v_pk_mul_f32 v[182:183], v[114:115], v[130:131]
	v_pk_mul_f32 v[184:185], v[180:181], v[144:145]
	v_pk_mul_f32 v[186:187], v[182:183], v[142:143]
	v_pk_mul_f32 v[144:145], v[176:177], v[144:145]
	v_pk_mul_f32 v[142:143], v[178:179], v[142:143]
	v_pk_fma_f32 v[184:185], v[176:177], v[140:141], v[184:185] neg_lo:[0,0,1] neg_hi:[0,0,1]
	v_pk_fma_f32 v[186:187], v[178:179], v[138:139], v[186:187] neg_lo:[0,0,1] neg_hi:[0,0,1]
	v_pk_fma_f32 v[140:141], v[140:141], v[180:181], v[144:145]
	v_pk_fma_f32 v[138:139], v[138:139], v[182:183], v[142:143]
	v_cvt_pk_bf16_f32 v142, v186, v187
	v_cvt_pk_bf16_f32 v143, v184, v185
	v_mul_f32_e32 v175, v111, v111
	v_cvt_pk_bf16_f32 v138, v138, v139
	v_cvt_pk_bf16_f32 v139, v140, v141
	v_mul_f32_e32 v176, v113, v113
	v_cndmask_b32_e64 v140, v143, v139, s[36:37]
	v_cndmask_b32_e64 v141, v142, v138, s[36:37]
	ds_bpermute_b32 v140, v218, v140
	ds_bpermute_b32 v144, v218, v141
	v_fmac_f32_e32 v175, v110, v110
	v_fmac_f32_e32 v176, v112, v112
	v_add_f32_e32 v175, v175, v176
	s_waitcnt lgkmcnt(0)
	v_cndmask_b32_e64 v141, v139, v140, s[36:37]
	v_cndmask_b32_e64 v139, v140, v143, s[36:37]
	v_cndmask_b32_e64 v140, v138, v144, s[36:37]
	v_cndmask_b32_e64 v138, v144, v142, s[36:37]
	flat_store_dwordx4 v[166:167], v[138:141] offset:256 sc1
	v_or_b32_e32 v166, 16, v162
	v_ashrrev_i32_e32 v167, 31, v166
	v_lshlrev_b64 v[138:139], 8, v[166:167]
	v_lshl_add_u64 v[140:141], v[154:155], 0, v[138:139]
	v_lshl_add_u64 v[142:143], v[156:157], 0, v[138:139]
	flat_load_dwordx4 v[138:141], v[140:141]
	s_nop 0
	flat_load_dwordx4 v[142:145], v[142:143]
	v_mul_f32_e32 v176, v107, v107
	v_fmac_f32_e32 v176, v106, v106
	v_add_f32_e32 v175, v175, v176
	v_mul_f32_e32 v176, v109, v109
	v_fmac_f32_e32 v176, v108, v108
	v_add_f32_e32 v175, v176, v175
	ds_bpermute_b32 v176, v218, v175
	s_waitcnt lgkmcnt(0)
	v_add_f32_e32 v175, v175, v176
	ds_bpermute_b32 v176, v219, v175
	s_and_saveexec_b64 s[14:15], s[34:35]
	s_cbranch_execz .LBB0_416
	s_waitcnt lgkmcnt(0)
	v_add_f32_e32 v175, v175, v176
	ds_write_b32 v174, v175 offset:512
; __device__ __forceinline__ unsigned cvt_pk_bf16(float lo, float hi) { unsigned r; asm volatile("v_cvt_pk_bf16_f32 %0, %1, %2" : "=v"(r) : "v"(lo), "v"(hi)); return r; }
;     __device__ __forceinline__ void operator()(const f32x4 (&acc)[2][2][4][2], const Unit& u, int wr, int wc, int fr, int fq, PG8_LAS float* xt) const {
;     ...
;                 for (int m = 0; m < 4; ++m) { const int row = row0 + ai * HALF + m * 16;
;                     const f32x4 cs = *(const f32x4*)(cosT + (size_t)row * 64 + d1), sn = *(const f32x4*)(sinT + (size_t)row * 64 + d1);
; #pragma unroll
;                     for (int bj = 0; bj < 2; ++bj) { const f32x4 x1 = acc[ai][bj][m][0], x2 = acc[ai][bj][m][1];
;                         float s = (x1[0] * x1[0] + x1[1] * x1[1]) + (x1[2] * x1[2] + x1[3] * x1[3]) + (x2[0] * x2[0] + x2[1] * x2[1]) + (x2[2] * x2[2] + x2[3] * x2[3]);
;                         s += __shfl_xor(s, 16); s += __shfl_xor(s, 32);
;                         const int hidx = (pn - 4) * 2 + bj;
;                         if (fq == 0) xt[((ai * HALF + wr * 64 + m * 16 + fr) * 2 + bj) * 4 + wc] = s;
;                         const f32x4 a1 = x1 * g1, a2 = x2 * g2;
;                         const f32x4 y1 = a1 * cs - a2 * sn, y2 = a2 * cs + a1 * sn;
;                         u32x2 w1; w1.x = cvt_pk_bf16(y1[0], y1[1]); w1.y = cvt_pk_bf16(y1[2], y1[3]);
;                         u32x2 w2; w2.x = cvt_pk_bf16(y2[0], y2[1]); w2.y = cvt_pk_bf16(y2[2], y2[3]);
;                         const bool odd = (fq & 1) != 0;
;                         const unsigned sx = odd ? w1.x : w2.x, sy = odd ? w1.y : w2.y;
;                         const unsigned rx = (unsigned)__shfl_xor((int)sx, 16), ry = (unsigned)__shfl_xor((int)sy, 16);
;                         u32x4 wv; if (odd) { wv.x = rx; wv.y = ry; wv.z = w2.x; wv.w = w2.y; } else { wv.x = w1.x; wv.y = w1.y; wv.z = rx; wv.w = ry; }
;                         bf16_t* p = O + (size_t)row * 1024 + (hidx & 7) * 128 + (odd ? (64 + d1 - 4) : d1);
;                         *(u32x4*)p = wv; } }
.LBB0_416:
	s_or_b64 exec, exec, s[14:15]
	v_pk_mul_f32 v[182:183], v[106:107], v[130:131]
	v_pk_mul_f32 v[178:179], v[110:111], v[134:135]
	v_pk_mul_f32 v[180:181], v[108:109], v[132:133]
	s_waitcnt vmcnt(0)
	v_pk_mul_f32 v[186:187], v[182:183], v[142:143]
	s_waitcnt lgkmcnt(0)
	v_pk_mul_f32 v[176:177], v[112:113], v[136:137]
	v_pk_mul_f32 v[184:185], v[180:181], v[144:145]
	v_pk_fma_f32 v[186:187], v[178:179], v[138:139], v[186:187] neg_lo:[0,0,1] neg_hi:[0,0,1]
	v_pk_mul_f32 v[178:179], v[178:179], v[142:143]
	v_pk_fma_f32 v[184:185], v[176:177], v[140:141], v[184:185] neg_lo:[0,0,1] neg_hi:[0,0,1]
	v_pk_mul_f32 v[176:177], v[176:177], v[144:145]
	v_pk_fma_f32 v[178:179], v[182:183], v[138:139], v[178:179]
	v_pk_fma_f32 v[176:177], v[180:181], v[140:141], v[176:177]
	v_cvt_pk_bf16_f32 v182, v186, v187
	v_cvt_pk_bf16_f32 v175, v184, v185
	v_cvt_pk_bf16_f32 v178, v178, v179
	v_mul_f32_e32 v179, v103, v103
	v_mul_f32_e32 v180, v105, v105
	v_fmac_f32_e32 v179, v102, v102
	v_fmac_f32_e32 v180, v104, v104
	v_add_f32_e32 v179, v179, v180
	v_mul_f32_e32 v180, v99, v99
	v_fmac_f32_e32 v180, v98, v98
	v_add_f32_e32 v179, v179, v180
	v_mul_f32_e32 v180, v101, v101
	v_fmac_f32_e32 v180, v100, v100
	v_cvt_pk_bf16_f32 v176, v176, v177
	v_add_f32_e32 v180, v180, v179
	v_cndmask_b32_e64 v177, v175, v176, s[36:37]
	ds_bpermute_b32 v177, v218, v177
	ds_bpermute_b32 v183, v218, v180
	v_cndmask_b32_e64 v179, v182, v178, s[36:37]
	ds_bpermute_b32 v184, v218, v179
	v_lshlrev_b64 v[166:167], 11, v[166:167]
	s_waitcnt lgkmcnt(2)
	v_cndmask_b32_e64 v179, v177, v175, s[36:37]
	s_waitcnt lgkmcnt(1)
	v_add_f32_e32 v175, v180, v183
	v_cndmask_b32_e64 v181, v176, v177, s[36:37]
	ds_bpermute_b32 v176, v219, v175
	v_lshl_add_u64 v[166:167], v[164:165], 0, v[166:167]
	s_waitcnt lgkmcnt(1)
	v_cndmask_b32_e64 v180, v178, v184, s[36:37]
	v_cndmask_b32_e64 v178, v184, v182, s[36:37]
	v_lshl_add_u64 v[166:167], v[166:167], 0, s[76:77]
	flat_store_dwordx4 v[166:167], v[178:181] sc1
	s_and_saveexec_b64 s[14:15], s[34:35]
	s_cbranch_execz .LBB0_418
	s_waitcnt lgkmcnt(0)
	v_add_f32_e32 v175, v175, v176
	ds_write_b32 v174, v175 offset:528
.LBB0_418:
	s_or_b64 exec, exec, s[14:15]
	s_waitcnt lgkmcnt(0)
	v_pk_mul_f32 v[176:177], v[104:105], v[136:137]
	v_pk_mul_f32 v[178:179], v[102:103], v[134:135]
	v_pk_mul_f32 v[180:181], v[100:101], v[132:133]
	v_pk_mul_f32 v[182:183], v[98:99], v[130:131]
	v_pk_mul_f32 v[184:185], v[180:181], v[144:145]
	v_pk_mul_f32 v[186:187], v[182:183], v[142:143]
	v_pk_mul_f32 v[144:145], v[176:177], v[144:145]
	v_pk_mul_f32 v[142:143], v[178:179], v[142:143]
	v_pk_fma_f32 v[184:185], v[176:177], v[140:141], v[184:185] neg_lo:[0,0,1] neg_hi:[0,0,1]
	v_pk_fma_f32 v[186:187], v[178:179], v[138:139], v[186:187] neg_lo:[0,0,1] neg_hi:[0,0,1]
	v_pk_fma_f32 v[140:141], v[180:181], v[140:141], v[144:145]
	v_pk_fma_f32 v[138:139], v[182:183], v[138:139], v[142:143]
	v_cvt_pk_bf16_f32 v142, v186, v187
	v_cvt_pk_bf16_f32 v143, v184, v185
	v_mul_f32_e32 v175, v93, v93
	v_cvt_pk_bf16_f32 v138, v138, v139
	v_cvt_pk_bf16_f32 v139, v140, v141
	v_mul_f32_e32 v176, v95, v95
	v_cndmask_b32_e64 v140, v143, v139, s[36:37]
	v_cndmask_b32_e64 v141, v142, v138, s[36:37]
	ds_bpermute_b32 v140, v218, v140
	ds_bpermute_b32 v144, v218, v141
	v_fmac_f32_e32 v175, v92, v92
	v_fmac_f32_e32 v176, v94, v94
	v_add_f32_e32 v175, v175, v176
	s_waitcnt lgkmcnt(0)
	v_cndmask_b32_e64 v141, v139, v140, s[36:37]
	v_cndmask_b32_e64 v139, v140, v143, s[36:37]
	v_cndmask_b32_e64 v140, v138, v144, s[36:37]
	v_cndmask_b32_e64 v138, v144, v142, s[36:37]
	flat_store_dwordx4 v[166:167], v[138:141] offset:256 sc1
	v_or_b32_e32 v166, 32, v162
	v_ashrrev_i32_e32 v167, 31, v166
	v_lshlrev_b64 v[138:139], 8, v[166:167]
	v_lshl_add_u64 v[140:141], v[154:155], 0, v[138:139]
	v_lshl_add_u64 v[142:143], v[156:157], 0, v[138:139]
	flat_load_dwordx4 v[138:141], v[140:141]
	s_nop 0
	flat_load_dwordx4 v[142:145], v[142:143]
	v_mul_f32_e32 v176, v89, v89
	v_fmac_f32_e32 v176, v88, v88
	v_add_f32_e32 v175, v175, v176
	v_mul_f32_e32 v176, v91, v91
	v_fmac_f32_e32 v176, v90, v90
	v_add_f32_e32 v175, v176, v175
	ds_bpermute_b32 v176, v218, v175
	s_waitcnt lgkmcnt(0)
	v_add_f32_e32 v175, v175, v176
	ds_bpermute_b32 v176, v219, v175
	s_and_saveexec_b64 s[14:15], s[34:35]
	s_cbranch_execz .LBB0_420
	s_waitcnt lgkmcnt(0)
	v_add_f32_e32 v175, v175, v176
	ds_write_b32 v174, v175 offset:1024
.LBB0_420:
	s_or_b64 exec, exec, s[14:15]
	v_pk_mul_f32 v[182:183], v[88:89], v[130:131]
	v_pk_mul_f32 v[178:179], v[92:93], v[134:135]
	v_pk_mul_f32 v[180:181], v[90:91], v[132:133]
	s_waitcnt vmcnt(0)
	v_pk_mul_f32 v[186:187], v[182:183], v[142:143]
	s_waitcnt lgkmcnt(0)
	v_pk_mul_f32 v[176:177], v[94:95], v[136:137]
	v_pk_mul_f32 v[184:185], v[180:181], v[144:145]
	v_pk_fma_f32 v[186:187], v[178:179], v[138:139], v[186:187] neg_lo:[0,0,1] neg_hi:[0,0,1]
	v_pk_mul_f32 v[178:179], v[178:179], v[142:143]
	v_pk_fma_f32 v[184:185], v[176:177], v[140:141], v[184:185] neg_lo:[0,0,1] neg_hi:[0,0,1]
	v_pk_mul_f32 v[176:177], v[176:177], v[144:145]
	v_pk_fma_f32 v[178:179], v[182:183], v[138:139], v[178:179]
	v_pk_fma_f32 v[176:177], v[180:181], v[140:141], v[176:177]
	v_cvt_pk_bf16_f32 v182, v186, v187
	v_cvt_pk_bf16_f32 v175, v184, v185
	v_cvt_pk_bf16_f32 v178, v178, v179
	v_mul_f32_e32 v179, v85, v85
	v_mul_f32_e32 v180, v87, v87
	v_fmac_f32_e32 v179, v84, v84
	v_fmac_f32_e32 v180, v86, v86
	v_add_f32_e32 v179, v179, v180
	v_mul_f32_e32 v180, v81, v81
	v_fmac_f32_e32 v180, v80, v80
	v_add_f32_e32 v179, v179, v180
	v_mul_f32_e32 v180, v83, v83
	v_fmac_f32_e32 v180, v82, v82
	v_cvt_pk_bf16_f32 v176, v176, v177
	v_add_f32_e32 v180, v180, v179
	v_cndmask_b32_e64 v177, v175, v176, s[36:37]
	ds_bpermute_b32 v177, v218, v177
	ds_bpermute_b32 v183, v218, v180
	v_cndmask_b32_e64 v179, v182, v178, s[36:37]
	ds_bpermute_b32 v184, v218, v179
	v_lshlrev_b64 v[166:167], 11, v[166:167]
	s_waitcnt lgkmcnt(2)
	v_cndmask_b32_e64 v179, v177, v175, s[36:37]
	s_waitcnt lgkmcnt(1)
	v_add_f32_e32 v175, v180, v183
	v_cndmask_b32_e64 v181, v176, v177, s[36:37]
	ds_bpermute_b32 v176, v219, v175
	v_lshl_add_u64 v[166:167], v[164:165], 0, v[166:167]
	s_waitcnt lgkmcnt(1)
	v_cndmask_b32_e64 v180, v178, v184, s[36:37]
	v_cndmask_b32_e64 v178, v184, v182, s[36:37]
	v_lshl_add_u64 v[166:167], v[166:167], 0, s[76:77]
	flat_store_dwordx4 v[166:167], v[178:181] sc1
	s_and_saveexec_b64 s[14:15], s[34:35]
	s_cbranch_execz .LBB0_422
	s_waitcnt lgkmcnt(0)
	v_add_f32_e32 v175, v175, v176
	ds_write_b32 v174, v175 offset:1040
; __device__ __forceinline__ unsigned cvt_pk_bf16(float lo, float hi) { unsigned r; asm volatile("v_cvt_pk_bf16_f32 %0, %1, %2" : "=v"(r) : "v"(lo), "v"(hi)); return r; }
;     __device__ __forceinline__ void operator()(const f32x4 (&acc)[2][2][4][2], const Unit& u, int wr, int wc, int fr, int fq, PG8_LAS float* xt) const {
;     ...
;                 for (int m = 0; m < 4; ++m) { const int row = row0 + ai * HALF + m * 16;
;                     const f32x4 cs = *(const f32x4*)(cosT + (size_t)row * 64 + d1), sn = *(const f32x4*)(sinT + (size_t)row * 64 + d1);
; #pragma unroll
;                     for (int bj = 0; bj < 2; ++bj) { const f32x4 x1 = acc[ai][bj][m][0], x2 = acc[ai][bj][m][1];
;                         float s = (x1[0] * x1[0] + x1[1] * x1[1]) + (x1[2] * x1[2] + x1[3] * x1[3]) + (x2[0] * x2[0] + x2[1] * x2[1]) + (x2[2] * x2[2] + x2[3] * x2[3]);
;                         s += __shfl_xor(s, 16); s += __shfl_xor(s, 32);
;                         const int hidx = (pn - 4) * 2 + bj;
;                         if (fq == 0) xt[((ai * HALF + wr * 64 + m * 16 + fr) * 2 + bj) * 4 + wc] = s;
;                         const f32x4 a1 = x1 * g1, a2 = x2 * g2;
;                         const f32x4 y1 = a1 * cs - a2 * sn, y2 = a2 * cs + a1 * sn;
;                         u32x2 w1; w1.x = cvt_pk_bf16(y1[0], y1[1]); w1.y = cvt_pk_bf16(y1[2], y1[3]);
;                         u32x2 w2; w2.x = cvt_pk_bf16(y2[0], y2[1]); w2.y = cvt_pk_bf16(y2[2], y2[3]);
;                         const bool odd = (fq & 1) != 0;
;                         const unsigned sx = odd ? w1.x : w2.x, sy = odd ? w1.y : w2.y;
;                         const unsigned rx = (unsigned)__shfl_xor((int)sx, 16), ry = (unsigned)__shfl_xor((int)sy, 16);
;                         u32x4 wv; if (odd) { wv.x = rx; wv.y = ry; wv.z = w2.x; wv.w = w2.y; } else { wv.x = w1.x; wv.y = w1.y; wv.z = rx; wv.w = ry; }
;                         bf16_t* p = O + (size_t)row * 1024 + (hidx & 7) * 128 + (odd ? (64 + d1 - 4) : d1);
;                         *(u32x4*)p = wv; } }
.LBB0_422:
	s_or_b64 exec, exec, s[14:15]
	s_waitcnt lgkmcnt(0)
	v_pk_mul_f32 v[176:177], v[86:87], v[136:137]
	v_pk_mul_f32 v[178:179], v[84:85], v[134:135]
	v_pk_mul_f32 v[180:181], v[82:83], v[132:133]
	v_pk_mul_f32 v[182:183], v[80:81], v[130:131]
	v_pk_mul_f32 v[184:185], v[180:181], v[144:145]
	v_pk_mul_f32 v[186:187], v[182:183], v[142:143]
	v_pk_mul_f32 v[144:145], v[176:177], v[144:145]
	v_pk_mul_f32 v[142:143], v[178:179], v[142:143]
	v_pk_fma_f32 v[184:185], v[176:177], v[140:141], v[184:185] neg_lo:[0,0,1] neg_hi:[0,0,1]
	v_pk_fma_f32 v[186:187], v[178:179], v[138:139], v[186:187] neg_lo:[0,0,1] neg_hi:[0,0,1]
	v_pk_fma_f32 v[140:141], v[180:181], v[140:141], v[144:145]
	v_pk_fma_f32 v[138:139], v[182:183], v[138:139], v[142:143]
	v_cvt_pk_bf16_f32 v142, v186, v187
	v_cvt_pk_bf16_f32 v143, v184, v185
	v_mul_f32_e32 v175, v77, v77
	v_cvt_pk_bf16_f32 v138, v138, v139
	v_cvt_pk_bf16_f32 v139, v140, v141
	v_mul_f32_e32 v176, v79, v79
	v_cndmask_b32_e64 v140, v143, v139, s[36:37]
	v_cndmask_b32_e64 v141, v142, v138, s[36:37]
	ds_bpermute_b32 v140, v218, v140
	ds_bpermute_b32 v144, v218, v141
	v_fmac_f32_e32 v175, v76, v76
	v_fmac_f32_e32 v176, v78, v78
	v_add_f32_e32 v175, v175, v176
	s_waitcnt lgkmcnt(0)
	v_cndmask_b32_e64 v141, v139, v140, s[36:37]
	v_cndmask_b32_e64 v139, v140, v143, s[36:37]
	v_cndmask_b32_e64 v140, v138, v144, s[36:37]
	v_cndmask_b32_e64 v138, v144, v142, s[36:37]
	flat_store_dwordx4 v[166:167], v[138:141] offset:256 sc1
	v_or_b32_e32 v166, 48, v162
	v_ashrrev_i32_e32 v167, 31, v166
	v_lshlrev_b64 v[138:139], 8, v[166:167]
	v_lshl_add_u64 v[140:141], v[154:155], 0, v[138:139]
	v_lshl_add_u64 v[142:143], v[156:157], 0, v[138:139]
	flat_load_dwordx4 v[138:141], v[140:141]
	s_nop 0
	flat_load_dwordx4 v[142:145], v[142:143]
	v_mul_f32_e32 v176, v73, v73
	v_fmac_f32_e32 v176, v72, v72
	v_add_f32_e32 v175, v175, v176
	v_mul_f32_e32 v176, v75, v75
	v_fmac_f32_e32 v176, v74, v74
	v_add_f32_e32 v175, v176, v175
	ds_bpermute_b32 v176, v218, v175
	s_waitcnt lgkmcnt(0)
	v_add_f32_e32 v175, v175, v176
	ds_bpermute_b32 v176, v219, v175
	s_and_saveexec_b64 s[14:15], s[34:35]
	s_cbranch_execz .LBB0_424
	s_waitcnt lgkmcnt(0)
	v_add_f32_e32 v175, v175, v176
	ds_write_b32 v174, v175 offset:1536
.LBB0_424:
	s_or_b64 exec, exec, s[14:15]
	v_pk_mul_f32 v[182:183], v[72:73], v[130:131]
	v_pk_mul_f32 v[178:179], v[76:77], v[134:135]
	v_pk_mul_f32 v[180:181], v[74:75], v[132:133]
	s_waitcnt vmcnt(0)
	v_pk_mul_f32 v[186:187], v[182:183], v[142:143]
	s_waitcnt lgkmcnt(0)
	v_pk_mul_f32 v[176:177], v[78:79], v[136:137]
	v_pk_mul_f32 v[184:185], v[180:181], v[144:145]
	v_pk_fma_f32 v[186:187], v[178:179], v[138:139], v[186:187] neg_lo:[0,0,1] neg_hi:[0,0,1]
	v_pk_mul_f32 v[178:179], v[178:179], v[142:143]
	v_pk_fma_f32 v[184:185], v[176:177], v[140:141], v[184:185] neg_lo:[0,0,1] neg_hi:[0,0,1]
	v_pk_mul_f32 v[176:177], v[176:177], v[144:145]
	v_pk_fma_f32 v[178:179], v[182:183], v[138:139], v[178:179]
	v_pk_fma_f32 v[176:177], v[180:181], v[140:141], v[176:177]
	v_cvt_pk_bf16_f32 v182, v186, v187
	v_cvt_pk_bf16_f32 v175, v184, v185
	v_cvt_pk_bf16_f32 v178, v178, v179
	v_mul_f32_e32 v179, v69, v69
	v_mul_f32_e32 v180, v71, v71
	v_fmac_f32_e32 v179, v68, v68
	v_fmac_f32_e32 v180, v70, v70
	v_add_f32_e32 v179, v179, v180
	v_mul_f32_e32 v180, v65, v65
	v_fmac_f32_e32 v180, v64, v64
	v_add_f32_e32 v179, v179, v180
	v_mul_f32_e32 v180, v67, v67
	v_fmac_f32_e32 v180, v66, v66
	v_cvt_pk_bf16_f32 v176, v176, v177
	v_add_f32_e32 v180, v180, v179
	v_cndmask_b32_e64 v177, v175, v176, s[36:37]
	ds_bpermute_b32 v177, v218, v177
	ds_bpermute_b32 v183, v218, v180
	v_cndmask_b32_e64 v179, v182, v178, s[36:37]
	ds_bpermute_b32 v184, v218, v179
	v_lshlrev_b64 v[166:167], 11, v[166:167]
	s_waitcnt lgkmcnt(2)
	v_cndmask_b32_e64 v179, v177, v175, s[36:37]
	s_waitcnt lgkmcnt(1)
	v_add_f32_e32 v175, v180, v183
	v_cndmask_b32_e64 v181, v176, v177, s[36:37]
	ds_bpermute_b32 v176, v219, v175
	v_lshl_add_u64 v[166:167], v[164:165], 0, v[166:167]
	s_waitcnt lgkmcnt(1)
	v_cndmask_b32_e64 v180, v178, v184, s[36:37]
	v_cndmask_b32_e64 v178, v184, v182, s[36:37]
	v_lshl_add_u64 v[166:167], v[166:167], 0, s[76:77]
	flat_store_dwordx4 v[166:167], v[178:181] sc1
	s_and_saveexec_b64 s[14:15], s[34:35]
	s_cbranch_execz .LBB0_426
	s_waitcnt lgkmcnt(0)
	v_add_f32_e32 v175, v175, v176
	ds_write_b32 v174, v175 offset:1552
.LBB0_426:
	s_or_b64 exec, exec, s[14:15]
	s_waitcnt lgkmcnt(0)
	v_pk_mul_f32 v[176:177], v[70:71], v[136:137]
	v_pk_mul_f32 v[178:179], v[68:69], v[134:135]
	v_pk_mul_f32 v[180:181], v[66:67], v[132:133]
	v_pk_mul_f32 v[182:183], v[64:65], v[130:131]
	v_pk_mul_f32 v[184:185], v[180:181], v[144:145]
	v_pk_mul_f32 v[186:187], v[182:183], v[142:143]
	v_pk_mul_f32 v[144:145], v[176:177], v[144:145]
	v_pk_mul_f32 v[142:143], v[178:179], v[142:143]
	v_pk_fma_f32 v[184:185], v[176:177], v[140:141], v[184:185] neg_lo:[0,0,1] neg_hi:[0,0,1]
	v_pk_fma_f32 v[186:187], v[178:179], v[138:139], v[186:187] neg_lo:[0,0,1] neg_hi:[0,0,1]
	v_pk_fma_f32 v[140:141], v[180:181], v[140:141], v[144:145]
	v_pk_fma_f32 v[138:139], v[182:183], v[138:139], v[142:143]
	v_cvt_pk_bf16_f32 v142, v186, v187
	v_cvt_pk_bf16_f32 v143, v184, v185
	v_mul_f32_e32 v175, v61, v61
	v_cvt_pk_bf16_f32 v138, v138, v139
	v_cvt_pk_bf16_f32 v139, v140, v141
	v_mul_f32_e32 v176, v63, v63
	v_cndmask_b32_e64 v140, v143, v139, s[36:37]
	v_cndmask_b32_e64 v141, v142, v138, s[36:37]
	ds_bpermute_b32 v140, v218, v140
	ds_bpermute_b32 v144, v218, v141
	v_fmac_f32_e32 v175, v60, v60
	v_fmac_f32_e32 v176, v62, v62
	v_add_f32_e32 v175, v175, v176
	s_waitcnt lgkmcnt(0)
	v_cndmask_b32_e64 v141, v139, v140, s[36:37]
	v_cndmask_b32_e64 v139, v140, v143, s[36:37]
	v_cndmask_b32_e64 v140, v138, v144, s[36:37]
	v_cndmask_b32_e64 v138, v144, v142, s[36:37]
	flat_store_dwordx4 v[166:167], v[138:141] offset:256 sc1
	v_add_u32_e32 v166, 0x80, v162
	v_ashrrev_i32_e32 v167, 31, v166
	v_lshlrev_b64 v[138:139], 8, v[166:167]
	v_lshl_add_u64 v[140:141], v[154:155], 0, v[138:139]
	v_lshl_add_u64 v[142:143], v[156:157], 0, v[138:139]
	flat_load_dwordx4 v[138:141], v[140:141]
	s_nop 0
	flat_load_dwordx4 v[142:145], v[142:143]
	v_mul_f32_e32 v176, v57, v57
	v_fmac_f32_e32 v176, v56, v56
	v_add_f32_e32 v175, v175, v176
	v_mul_f32_e32 v176, v59, v59
	v_fmac_f32_e32 v176, v58, v58
	v_add_f32_e32 v175, v176, v175
	ds_bpermute_b32 v176, v218, v175
	s_waitcnt lgkmcnt(0)
	v_add_f32_e32 v175, v175, v176
	ds_bpermute_b32 v176, v219, v175
	s_and_saveexec_b64 s[14:15], s[34:35]
	s_cbranch_execz .LBB0_428
	s_waitcnt lgkmcnt(0)
	v_add_f32_e32 v175, v175, v176
	ds_write_b32 v174, v175 offset:4096
; __device__ __forceinline__ unsigned cvt_pk_bf16(float lo, float hi) { unsigned r; asm volatile("v_cvt_pk_bf16_f32 %0, %1, %2" : "=v"(r) : "v"(lo), "v"(hi)); return r; }
;     __device__ __forceinline__ void operator()(const f32x4 (&acc)[2][2][4][2], const Unit& u, int wr, int wc, int fr, int fq, PG8_LAS float* xt) const {
;     ...
;                 for (int m = 0; m < 4; ++m) { const int row = row0 + ai * HALF + m * 16;
;                     const f32x4 cs = *(const f32x4*)(cosT + (size_t)row * 64 + d1), sn = *(const f32x4*)(sinT + (size_t)row * 64 + d1);
; #pragma unroll
;                     for (int bj = 0; bj < 2; ++bj) { const f32x4 x1 = acc[ai][bj][m][0], x2 = acc[ai][bj][m][1];
;                         float s = (x1[0] * x1[0] + x1[1] * x1[1]) + (x1[2] * x1[2] + x1[3] * x1[3]) + (x2[0] * x2[0] + x2[1] * x2[1]) + (x2[2] * x2[2] + x2[3] * x2[3]);
;                         s += __shfl_xor(s, 16); s += __shfl_xor(s, 32);
;                         const int hidx = (pn - 4) * 2 + bj;
;                         if (fq == 0) xt[((ai * HALF + wr * 64 + m * 16 + fr) * 2 + bj) * 4 + wc] = s;
;                         const f32x4 a1 = x1 * g1, a2 = x2 * g2;
;                         const f32x4 y1 = a1 * cs - a2 * sn, y2 = a2 * cs + a1 * sn;
;                         u32x2 w1; w1.x = cvt_pk_bf16(y1[0], y1[1]); w1.y = cvt_pk_bf16(y1[2], y1[3]);
;                         u32x2 w2; w2.x = cvt_pk_bf16(y2[0], y2[1]); w2.y = cvt_pk_bf16(y2[2], y2[3]);
;                         const bool odd = (fq & 1) != 0;
;                         const unsigned sx = odd ? w1.x : w2.x, sy = odd ? w1.y : w2.y;
;                         const unsigned rx = (unsigned)__shfl_xor((int)sx, 16), ry = (unsigned)__shfl_xor((int)sy, 16);
;                         u32x4 wv; if (odd) { wv.x = rx; wv.y = ry; wv.z = w2.x; wv.w = w2.y; } else { wv.x = w1.x; wv.y = w1.y; wv.z = rx; wv.w = ry; }
;                         bf16_t* p = O + (size_t)row * 1024 + (hidx & 7) * 128 + (odd ? (64 + d1 - 4) : d1);
;                         *(u32x4*)p = wv; } }
.LBB0_428:
	s_or_b64 exec, exec, s[14:15]
	v_pk_mul_f32 v[182:183], v[56:57], v[130:131]
	v_pk_mul_f32 v[178:179], v[60:61], v[134:135]
	v_pk_mul_f32 v[180:181], v[58:59], v[132:133]
	s_waitcnt vmcnt(0)
	v_pk_mul_f32 v[186:187], v[182:183], v[142:143]
	s_waitcnt lgkmcnt(0)
	v_pk_mul_f32 v[176:177], v[62:63], v[136:137]
	v_pk_mul_f32 v[184:185], v[180:181], v[144:145]
	v_pk_fma_f32 v[186:187], v[178:179], v[138:139], v[186:187] neg_lo:[0,0,1] neg_hi:[0,0,1]
	v_pk_mul_f32 v[178:179], v[178:179], v[142:143]
	v_pk_fma_f32 v[184:185], v[176:177], v[140:141], v[184:185] neg_lo:[0,0,1] neg_hi:[0,0,1]
	v_pk_mul_f32 v[176:177], v[176:177], v[144:145]
	v_pk_fma_f32 v[178:179], v[182:183], v[138:139], v[178:179]
	v_pk_fma_f32 v[176:177], v[180:181], v[140:141], v[176:177]
	v_cvt_pk_bf16_f32 v182, v186, v187
	v_cvt_pk_bf16_f32 v175, v184, v185
	v_cvt_pk_bf16_f32 v178, v178, v179
	v_mul_f32_e32 v179, v53, v53
	v_mul_f32_e32 v180, v55, v55
	v_fmac_f32_e32 v179, v52, v52
	v_fmac_f32_e32 v180, v54, v54
	v_add_f32_e32 v179, v179, v180
	v_mul_f32_e32 v180, v49, v49
	v_fmac_f32_e32 v180, v48, v48
	v_add_f32_e32 v179, v179, v180
	v_mul_f32_e32 v180, v51, v51
	v_fmac_f32_e32 v180, v50, v50
	v_cvt_pk_bf16_f32 v176, v176, v177
	v_add_f32_e32 v180, v180, v179
	v_cndmask_b32_e64 v177, v175, v176, s[36:37]
	ds_bpermute_b32 v177, v218, v177
	ds_bpermute_b32 v183, v218, v180
	v_cndmask_b32_e64 v179, v182, v178, s[36:37]
	ds_bpermute_b32 v184, v218, v179
	v_lshlrev_b64 v[166:167], 11, v[166:167]
	s_waitcnt lgkmcnt(2)
	v_cndmask_b32_e64 v179, v177, v175, s[36:37]
	s_waitcnt lgkmcnt(1)
	v_add_f32_e32 v175, v180, v183
	v_cndmask_b32_e64 v181, v176, v177, s[36:37]
	ds_bpermute_b32 v176, v219, v175
	v_lshl_add_u64 v[166:167], v[164:165], 0, v[166:167]
	s_waitcnt lgkmcnt(1)
	v_cndmask_b32_e64 v180, v178, v184, s[36:37]
	v_cndmask_b32_e64 v178, v184, v182, s[36:37]
	v_lshl_add_u64 v[166:167], v[166:167], 0, s[76:77]
	flat_store_dwordx4 v[166:167], v[178:181] sc1
	s_and_saveexec_b64 s[14:15], s[34:35]
	s_cbranch_execz .LBB0_430
	s_waitcnt lgkmcnt(0)
	v_add_f32_e32 v175, v175, v176
	ds_write_b32 v174, v175 offset:4112
.LBB0_430:
	s_or_b64 exec, exec, s[14:15]
	s_waitcnt lgkmcnt(0)
	v_pk_mul_f32 v[176:177], v[54:55], v[136:137]
	v_pk_mul_f32 v[178:179], v[52:53], v[134:135]
	v_pk_mul_f32 v[180:181], v[50:51], v[132:133]
	v_pk_mul_f32 v[182:183], v[48:49], v[130:131]
	v_pk_mul_f32 v[184:185], v[180:181], v[144:145]
	v_pk_mul_f32 v[186:187], v[182:183], v[142:143]
	v_pk_mul_f32 v[144:145], v[176:177], v[144:145]
	v_pk_mul_f32 v[142:143], v[178:179], v[142:143]
	v_pk_fma_f32 v[184:185], v[176:177], v[140:141], v[184:185] neg_lo:[0,0,1] neg_hi:[0,0,1]
	v_pk_fma_f32 v[186:187], v[178:179], v[138:139], v[186:187] neg_lo:[0,0,1] neg_hi:[0,0,1]
	v_pk_fma_f32 v[140:141], v[180:181], v[140:141], v[144:145]
	v_pk_fma_f32 v[138:139], v[182:183], v[138:139], v[142:143]
	v_cvt_pk_bf16_f32 v142, v186, v187
	v_cvt_pk_bf16_f32 v143, v184, v185
	v_mul_f32_e32 v175, v45, v45
	v_cvt_pk_bf16_f32 v138, v138, v139
	v_cvt_pk_bf16_f32 v139, v140, v141
	v_mul_f32_e32 v176, v47, v47
	v_cndmask_b32_e64 v140, v143, v139, s[36:37]
	v_cndmask_b32_e64 v141, v142, v138, s[36:37]
	ds_bpermute_b32 v140, v218, v140
	ds_bpermute_b32 v144, v218, v141
	v_fmac_f32_e32 v175, v44, v44
	v_fmac_f32_e32 v176, v46, v46
	v_add_f32_e32 v175, v175, v176
	s_waitcnt lgkmcnt(0)
	v_cndmask_b32_e64 v141, v139, v140, s[36:37]
	v_cndmask_b32_e64 v139, v140, v143, s[36:37]
	v_cndmask_b32_e64 v140, v138, v144, s[36:37]
	v_cndmask_b32_e64 v138, v144, v142, s[36:37]
	flat_store_dwordx4 v[166:167], v[138:141] offset:256 sc1
	v_add_u32_e32 v166, 0x90, v162
	v_ashrrev_i32_e32 v167, 31, v166
	v_lshlrev_b64 v[138:139], 8, v[166:167]
	v_lshl_add_u64 v[140:141], v[154:155], 0, v[138:139]
	v_lshl_add_u64 v[142:143], v[156:157], 0, v[138:139]
	flat_load_dwordx4 v[138:141], v[140:141]
	s_nop 0
	flat_load_dwordx4 v[142:145], v[142:143]
	v_mul_f32_e32 v176, v41, v41
	v_fmac_f32_e32 v176, v40, v40
	v_add_f32_e32 v175, v175, v176
	v_mul_f32_e32 v176, v43, v43
	v_fmac_f32_e32 v176, v42, v42
	v_add_f32_e32 v175, v176, v175
	ds_bpermute_b32 v176, v218, v175
	s_waitcnt lgkmcnt(0)
	v_add_f32_e32 v175, v175, v176
	ds_bpermute_b32 v176, v219, v175
	s_and_saveexec_b64 s[14:15], s[34:35]
	s_cbranch_execz .LBB0_432
	s_waitcnt lgkmcnt(0)
	v_add_f32_e32 v175, v175, v176
	ds_write_b32 v174, v175 offset:4608
.LBB0_432:
	s_or_b64 exec, exec, s[14:15]
	v_pk_mul_f32 v[182:183], v[40:41], v[130:131]
	v_pk_mul_f32 v[178:179], v[44:45], v[134:135]
	v_pk_mul_f32 v[180:181], v[42:43], v[132:133]
	s_waitcnt vmcnt(0)
	v_pk_mul_f32 v[186:187], v[182:183], v[142:143]
	s_waitcnt lgkmcnt(0)
	v_pk_mul_f32 v[176:177], v[46:47], v[136:137]
	v_pk_mul_f32 v[184:185], v[180:181], v[144:145]
	v_pk_fma_f32 v[186:187], v[178:179], v[138:139], v[186:187] neg_lo:[0,0,1] neg_hi:[0,0,1]
	v_pk_mul_f32 v[178:179], v[178:179], v[142:143]
	v_pk_fma_f32 v[184:185], v[176:177], v[140:141], v[184:185] neg_lo:[0,0,1] neg_hi:[0,0,1]
	v_pk_mul_f32 v[176:177], v[176:177], v[144:145]
	v_pk_fma_f32 v[178:179], v[182:183], v[138:139], v[178:179]
	v_pk_fma_f32 v[176:177], v[180:181], v[140:141], v[176:177]
	v_cvt_pk_bf16_f32 v182, v186, v187
	v_cvt_pk_bf16_f32 v175, v184, v185
	v_cvt_pk_bf16_f32 v178, v178, v179
	v_mul_f32_e32 v179, v37, v37
	v_mul_f32_e32 v180, v39, v39
	v_fmac_f32_e32 v179, v36, v36
	v_fmac_f32_e32 v180, v38, v38
	v_add_f32_e32 v179, v179, v180
	v_mul_f32_e32 v180, v33, v33
	v_fmac_f32_e32 v180, v32, v32
	v_add_f32_e32 v179, v179, v180
	v_mul_f32_e32 v180, v35, v35
	v_fmac_f32_e32 v180, v34, v34
	v_cvt_pk_bf16_f32 v176, v176, v177
	v_add_f32_e32 v180, v180, v179
	v_cndmask_b32_e64 v177, v175, v176, s[36:37]
	ds_bpermute_b32 v177, v218, v177
	ds_bpermute_b32 v183, v218, v180
	v_cndmask_b32_e64 v179, v182, v178, s[36:37]
	ds_bpermute_b32 v184, v218, v179
	v_lshlrev_b64 v[166:167], 11, v[166:167]
	s_waitcnt lgkmcnt(2)
	v_cndmask_b32_e64 v179, v177, v175, s[36:37]
	s_waitcnt lgkmcnt(1)
	v_add_f32_e32 v175, v180, v183
	v_cndmask_b32_e64 v181, v176, v177, s[36:37]
	ds_bpermute_b32 v176, v219, v175
	v_lshl_add_u64 v[166:167], v[164:165], 0, v[166:167]
	s_waitcnt lgkmcnt(1)
	v_cndmask_b32_e64 v180, v178, v184, s[36:37]
	v_cndmask_b32_e64 v178, v184, v182, s[36:37]
	v_lshl_add_u64 v[166:167], v[166:167], 0, s[76:77]
	flat_store_dwordx4 v[166:167], v[178:181] sc1
	s_and_saveexec_b64 s[14:15], s[34:35]
	s_cbranch_execz .LBB0_434
	s_waitcnt lgkmcnt(0)
	v_add_f32_e32 v175, v175, v176
	ds_write_b32 v174, v175 offset:4624
; __device__ __forceinline__ unsigned cvt_pk_bf16(float lo, float hi) { unsigned r; asm volatile("v_cvt_pk_bf16_f32 %0, %1, %2" : "=v"(r) : "v"(lo), "v"(hi)); return r; }
;     __device__ __forceinline__ void operator()(const f32x4 (&acc)[2][2][4][2], const Unit& u, int wr, int wc, int fr, int fq, PG8_LAS float* xt) const {
;     ...
;                     for (int bj = 0; bj < 2; ++bj) { const f32x4 x1 = acc[ai][bj][m][0], x2 = acc[ai][bj][m][1];
;                         float s = (x1[0] * x1[0] + x1[1] * x1[1]) + (x1[2] * x1[2] + x1[3] * x1[3]) + (x2[0] * x2[0] + x2[1] * x2[1]) + (x2[2] * x2[2] + x2[3] * x2[3]);
;                         s += __shfl_xor(s, 16); s += __shfl_xor(s, 32);
;                         const int hidx = (pn - 4) * 2 + bj;
;                         if (fq == 0) xt[((ai * HALF + wr * 64 + m * 16 + fr) * 2 + bj) * 4 + wc] = s;
;                         const f32x4 a1 = x1 * g1, a2 = x2 * g2;
;                         const f32x4 y1 = a1 * cs - a2 * sn, y2 = a2 * cs + a1 * sn;
;                         u32x2 w1; w1.x = cvt_pk_bf16(y1[0], y1[1]); w1.y = cvt_pk_bf16(y1[2], y1[3]);
;                         u32x2 w2; w2.x = cvt_pk_bf16(y2[0], y2[1]); w2.y = cvt_pk_bf16(y2[2], y2[3]);
;                         const bool odd = (fq & 1) != 0;
;                         const unsigned sx = odd ? w1.x : w2.x, sy = odd ? w1.y : w2.y;
;                         const unsigned rx = (unsigned)__shfl_xor((int)sx, 16), ry = (unsigned)__shfl_xor((int)sy, 16);
;                         u32x4 wv; if (odd) { wv.x = rx; wv.y = ry; wv.z = w2.x; wv.w = w2.y; } else { wv.x = w1.x; wv.y = w1.y; wv.z = rx; wv.w = ry; }
;                         bf16_t* p = O + (size_t)row * 1024 + (hidx & 7) * 128 + (odd ? (64 + d1 - 4) : d1);
;                         *(u32x4*)p = wv; } }
.LBB0_434:
	s_or_b64 exec, exec, s[14:15]
	s_waitcnt lgkmcnt(0)
	v_pk_mul_f32 v[176:177], v[38:39], v[136:137]
	v_pk_mul_f32 v[178:179], v[36:37], v[134:135]
	v_pk_mul_f32 v[180:181], v[34:35], v[132:133]
	v_pk_mul_f32 v[182:183], v[32:33], v[130:131]
	v_pk_mul_f32 v[184:185], v[180:181], v[144:145]
	v_pk_mul_f32 v[186:187], v[182:183], v[142:143]
	v_pk_mul_f32 v[144:145], v[176:177], v[144:145]
	v_pk_mul_f32 v[142:143], v[178:179], v[142:143]
	v_pk_fma_f32 v[184:185], v[176:177], v[140:141], v[184:185] neg_lo:[0,0,1] neg_hi:[0,0,1]
	v_pk_fma_f32 v[186:187], v[178:179], v[138:139], v[186:187] neg_lo:[0,0,1] neg_hi:[0,0,1]
	v_pk_fma_f32 v[140:141], v[180:181], v[140:141], v[144:145]
	v_pk_fma_f32 v[138:139], v[182:183], v[138:139], v[142:143]
	v_cvt_pk_bf16_f32 v142, v186, v187
	v_cvt_pk_bf16_f32 v143, v184, v185
	v_mul_f32_e32 v175, v29, v29
	v_cvt_pk_bf16_f32 v138, v138, v139
	v_cvt_pk_bf16_f32 v139, v140, v141
	v_mul_f32_e32 v176, v31, v31
	v_cndmask_b32_e64 v140, v143, v139, s[36:37]
	v_cndmask_b32_e64 v141, v142, v138, s[36:37]
	ds_bpermute_b32 v140, v218, v140
	ds_bpermute_b32 v144, v218, v141
	v_fmac_f32_e32 v175, v28, v28
	v_fmac_f32_e32 v176, v30, v30
	v_add_f32_e32 v175, v175, v176
	s_waitcnt lgkmcnt(0)
	v_cndmask_b32_e64 v141, v139, v140, s[36:37]
	v_cndmask_b32_e64 v139, v140, v143, s[36:37]
	v_cndmask_b32_e64 v140, v138, v144, s[36:37]
	v_cndmask_b32_e64 v138, v144, v142, s[36:37]
	flat_store_dwordx4 v[166:167], v[138:141] offset:256 sc1
	v_add_u32_e32 v166, 0xa0, v162
	v_ashrrev_i32_e32 v167, 31, v166
	v_lshlrev_b64 v[138:139], 8, v[166:167]
	v_lshl_add_u64 v[140:141], v[154:155], 0, v[138:139]
	v_lshl_add_u64 v[142:143], v[156:157], 0, v[138:139]
	flat_load_dwordx4 v[138:141], v[140:141]
	s_nop 0
	flat_load_dwordx4 v[142:145], v[142:143]
	v_mul_f32_e32 v176, v25, v25
	v_fmac_f32_e32 v176, v24, v24
	v_add_f32_e32 v175, v175, v176
	v_mul_f32_e32 v176, v27, v27
	v_fmac_f32_e32 v176, v26, v26
	v_add_f32_e32 v175, v176, v175
	ds_bpermute_b32 v176, v218, v175
	s_waitcnt lgkmcnt(0)
	v_add_f32_e32 v175, v175, v176
	ds_bpermute_b32 v176, v219, v175
	s_and_saveexec_b64 s[14:15], s[34:35]
	s_cbranch_execz .LBB0_436
	s_waitcnt lgkmcnt(0)
	v_add_f32_e32 v175, v175, v176
	ds_write_b32 v174, v175 offset:5120
.LBB0_436:
	s_or_b64 exec, exec, s[14:15]
	v_pk_mul_f32 v[182:183], v[24:25], v[130:131]
	v_pk_mul_f32 v[178:179], v[28:29], v[134:135]
	v_pk_mul_f32 v[180:181], v[26:27], v[132:133]
	s_waitcnt vmcnt(0)
	v_pk_mul_f32 v[186:187], v[182:183], v[142:143]
	s_waitcnt lgkmcnt(0)
	v_pk_mul_f32 v[176:177], v[30:31], v[136:137]
	v_pk_mul_f32 v[184:185], v[180:181], v[144:145]
	v_pk_fma_f32 v[186:187], v[178:179], v[138:139], v[186:187] neg_lo:[0,0,1] neg_hi:[0,0,1]
	v_pk_mul_f32 v[178:179], v[178:179], v[142:143]
	v_pk_fma_f32 v[184:185], v[176:177], v[140:141], v[184:185] neg_lo:[0,0,1] neg_hi:[0,0,1]
	v_pk_mul_f32 v[176:177], v[176:177], v[144:145]
	v_pk_fma_f32 v[178:179], v[182:183], v[138:139], v[178:179]
	v_pk_fma_f32 v[176:177], v[180:181], v[140:141], v[176:177]
	v_cvt_pk_bf16_f32 v182, v186, v187
	v_cvt_pk_bf16_f32 v175, v184, v185
	v_cvt_pk_bf16_f32 v178, v178, v179
	v_mul_f32_e32 v179, v21, v21
	v_mul_f32_e32 v180, v23, v23
	v_fmac_f32_e32 v179, v20, v20
	v_fmac_f32_e32 v180, v22, v22
	v_add_f32_e32 v179, v179, v180
	v_mul_f32_e32 v180, v17, v17
	v_fmac_f32_e32 v180, v16, v16
	v_add_f32_e32 v179, v179, v180
	v_mul_f32_e32 v180, v19, v19
	v_fmac_f32_e32 v180, v18, v18
	v_cvt_pk_bf16_f32 v176, v176, v177
	v_add_f32_e32 v180, v180, v179
	v_cndmask_b32_e64 v177, v175, v176, s[36:37]
	ds_bpermute_b32 v177, v218, v177
	ds_bpermute_b32 v183, v218, v180
	v_cndmask_b32_e64 v179, v182, v178, s[36:37]
	ds_bpermute_b32 v184, v218, v179
	v_lshlrev_b64 v[166:167], 11, v[166:167]
	s_waitcnt lgkmcnt(2)
	v_cndmask_b32_e64 v179, v177, v175, s[36:37]
	s_waitcnt lgkmcnt(1)
	v_add_f32_e32 v175, v180, v183
	v_cndmask_b32_e64 v181, v176, v177, s[36:37]
	ds_bpermute_b32 v176, v219, v175
	v_lshl_add_u64 v[166:167], v[164:165], 0, v[166:167]
	s_waitcnt lgkmcnt(1)
	v_cndmask_b32_e64 v180, v178, v184, s[36:37]
	v_cndmask_b32_e64 v178, v184, v182, s[36:37]
	v_lshl_add_u64 v[166:167], v[166:167], 0, s[76:77]
	flat_store_dwordx4 v[166:167], v[178:181] sc1
	s_and_saveexec_b64 s[14:15], s[34:35]
	s_cbranch_execz .LBB0_438
	s_waitcnt lgkmcnt(0)
	v_add_f32_e32 v175, v175, v176
	ds_write_b32 v174, v175 offset:5136
; #define PG8_LAS __attribute__((address_space(3)))
;     __device__ __forceinline__ void operator()(const f32x4 (&acc)[2][2][4][2], const Unit& u, int wr, int wc, int fr, int fq, PG8_LAS float* xt) const {
;     ...
;                 for (int m = 0; m < 4; ++m) { const int row = row0 + ai * HALF + m * 16;
;                     const f32x4 cs = *(const f32x4*)(cosT + (size_t)row * 64 + d1), sn = *(const f32x4*)(sinT + (size_t)row * 64 + d1);
; #pragma unroll
;                     for (int bj = 0; bj < 2; ++bj) { const f32x4 x1 = acc[ai][bj][m][0], x2 = acc[ai][bj][m][1];
;                         float s = (x1[0] * x1[0] + x1[1] * x1[1]) + (x1[2] * x1[2] + x1[3] * x1[3]) + (x2[0] * x2[0] + x2[1] * x2[1]) + (x2[2] * x2[2] + x2[3] * x2[3]);
;                         s += __shfl_xor(s, 16); s += __shfl_xor(s, 32);
;                         const int hidx = (pn - 4) * 2 + bj;
;                         if (fq == 0) xt[((ai * HALF + wr * 64 + m * 16 + fr) * 2 + bj) * 4 + wc] = s;
;                         const f32x4 a1 = x1 * g1, a2 = x2 * g2;
;                         const f32x4 y1 = a1 * cs - a2 * sn, y2 = a2 * cs + a1 * sn;
;                         u32x2 w1; w1.x = cvt_pk_bf16(y1[0], y1[1]); w1.y = cvt_pk_bf16(y1[2], y1[3]);
;                         u32x2 w2; w2.x = cvt_pk_bf16(y2[0], y2[1]); w2.y = cvt_pk_bf16(y2[2], y2[3]);
;                         const bool odd = (fq & 1) != 0;
;                         const unsigned sx = odd ? w1.x : w2.x, sy = odd ? w1.y : w2.y;
;                         const unsigned rx = (unsigned)__shfl_xor((int)sx, 16), ry = (unsigned)__shfl_xor((int)sy, 16);
;                         u32x4 wv; if (odd) { wv.x = rx; wv.y = ry; wv.z = w2.x; wv.w = w2.y; } else { wv.x = w1.x; wv.y = w1.y; wv.z = rx; wv.w = ry; }
;                         bf16_t* p = O + (size_t)row * 1024 + (hidx & 7) * 128 + (odd ? (64 + d1 - 4) : d1);
;                         *(u32x4*)p = wv; } }
;             asm volatile("s_waitcnt lgkmcnt(0)" ::: "memory"); __builtin_amdgcn_s_barrier(); asm volatile("" ::: "memory");
;             const int tid = (wr * 4 + wc) * 64 + fq * 16 + fr;
;             { const f32x4 pq = *(const PG8_LAS f32x4*)(xt + tid * 4); ssq_qk[(size_t)(u.pm * BM + (tid >> 1)) * 16 + (pn - 4) * 2 + (tid & 1)] = (pq[0] + pq[1]) + (pq[2] + pq[3]); }
.LBB0_438:
	s_or_b64 exec, exec, s[14:15]
	s_waitcnt lgkmcnt(0)
	v_pk_mul_f32 v[176:177], v[22:23], v[136:137]
	v_pk_mul_f32 v[178:179], v[20:21], v[134:135]
	v_pk_mul_f32 v[180:181], v[18:19], v[132:133]
	v_pk_mul_f32 v[182:183], v[16:17], v[130:131]
	v_pk_mul_f32 v[184:185], v[180:181], v[144:145]
	v_pk_mul_f32 v[186:187], v[182:183], v[142:143]
	v_pk_mul_f32 v[144:145], v[176:177], v[144:145]
	v_pk_mul_f32 v[142:143], v[178:179], v[142:143]
	v_pk_fma_f32 v[184:185], v[176:177], v[140:141], v[184:185] neg_lo:[0,0,1] neg_hi:[0,0,1]
	v_pk_fma_f32 v[186:187], v[178:179], v[138:139], v[186:187] neg_lo:[0,0,1] neg_hi:[0,0,1]
	v_pk_fma_f32 v[140:141], v[180:181], v[140:141], v[144:145]
	v_pk_fma_f32 v[138:139], v[182:183], v[138:139], v[142:143]
	v_cvt_pk_bf16_f32 v142, v186, v187
	v_cvt_pk_bf16_f32 v143, v184, v185
	v_mul_f32_e32 v175, v13, v13
	v_cvt_pk_bf16_f32 v138, v138, v139
	v_cvt_pk_bf16_f32 v139, v140, v141
	v_mul_f32_e32 v176, v15, v15
	v_cndmask_b32_e64 v140, v143, v139, s[36:37]
	v_cndmask_b32_e64 v141, v142, v138, s[36:37]
	ds_bpermute_b32 v140, v218, v140
	ds_bpermute_b32 v144, v218, v141
	v_fmac_f32_e32 v175, v12, v12
	v_fmac_f32_e32 v176, v14, v14
	v_add_f32_e32 v175, v175, v176
	s_waitcnt lgkmcnt(0)
	v_cndmask_b32_e64 v141, v139, v140, s[36:37]
	v_cndmask_b32_e64 v139, v140, v143, s[36:37]
	v_cndmask_b32_e64 v140, v138, v144, s[36:37]
	v_cndmask_b32_e64 v138, v144, v142, s[36:37]
	flat_store_dwordx4 v[166:167], v[138:141] offset:256 sc1
	v_add_u32_e32 v166, 0xb0, v162
	v_ashrrev_i32_e32 v167, 31, v166
	v_lshlrev_b64 v[138:139], 8, v[166:167]
	v_lshl_add_u64 v[140:141], v[154:155], 0, v[138:139]
	v_lshl_add_u64 v[142:143], v[156:157], 0, v[138:139]
	flat_load_dwordx4 v[138:141], v[140:141]
	s_nop 0
	flat_load_dwordx4 v[142:145], v[142:143]
	v_mul_f32_e32 v176, v9, v9
	v_fmac_f32_e32 v176, v8, v8
	v_add_f32_e32 v175, v175, v176
	v_mul_f32_e32 v176, v11, v11
	v_fmac_f32_e32 v176, v10, v10
	v_add_f32_e32 v175, v176, v175
	ds_bpermute_b32 v176, v218, v175
	s_waitcnt lgkmcnt(0)
	v_add_f32_e32 v175, v175, v176
	ds_bpermute_b32 v176, v219, v175
	s_and_saveexec_b64 s[14:15], s[34:35]
	s_cbranch_execz .LBB0_440
	s_waitcnt lgkmcnt(0)
	v_add_f32_e32 v175, v175, v176
	ds_write_b32 v174, v175 offset:5632
.LBB0_440:
	s_or_b64 exec, exec, s[14:15]
	v_pk_mul_f32 v[180:181], v[8:9], v[130:131]
	v_lshlrev_b64 v[166:167], 11, v[166:167]
	s_waitcnt lgkmcnt(0)
	v_pk_mul_f32 v[176:177], v[12:13], v[134:135]
	v_pk_mul_f32 v[178:179], v[10:11], v[132:133]
	s_waitcnt vmcnt(0)
	v_pk_mul_f32 v[184:185], v[180:181], v[142:143]
	v_lshl_add_u64 v[164:165], v[164:165], 0, v[166:167]
	v_pk_mul_f32 v[166:167], v[14:15], v[136:137]
	v_pk_mul_f32 v[182:183], v[178:179], v[144:145]
	v_pk_fma_f32 v[184:185], v[176:177], v[138:139], v[184:185] neg_lo:[0,0,1] neg_hi:[0,0,1]
	v_pk_mul_f32 v[176:177], v[176:177], v[142:143]
	v_pk_fma_f32 v[182:183], v[166:167], v[140:141], v[182:183] neg_lo:[0,0,1] neg_hi:[0,0,1]
	v_pk_mul_f32 v[166:167], v[166:167], v[144:145]
	v_pk_fma_f32 v[176:177], v[180:181], v[138:139], v[176:177]
	v_pk_fma_f32 v[166:167], v[178:179], v[140:141], v[166:167]
	v_cvt_pk_bf16_f32 v175, v184, v185
	v_cvt_pk_bf16_f32 v178, v182, v183
	v_cvt_pk_bf16_f32 v176, v176, v177
	v_mul_f32_e32 v177, v5, v5
	v_mul_f32_e32 v179, v7, v7
	v_fmac_f32_e32 v177, v4, v4
	v_fmac_f32_e32 v179, v6, v6
	v_add_f32_e32 v177, v177, v179
	v_mul_f32_e32 v179, v1, v1
	v_fmac_f32_e32 v179, v0, v0
	v_add_f32_e32 v177, v177, v179
	v_mul_f32_e32 v179, v3, v3
	v_fmac_f32_e32 v179, v2, v2
	v_cvt_pk_bf16_f32 v166, v166, v167
	v_add_f32_e32 v180, v179, v177
	v_cndmask_b32_e64 v167, v178, v166, s[36:37]
	ds_bpermute_b32 v167, v218, v167
	ds_bpermute_b32 v181, v218, v180
	v_cndmask_b32_e64 v177, v175, v176, s[36:37]
	ds_bpermute_b32 v182, v218, v177
	v_lshl_add_u64 v[164:165], v[164:165], 0, s[76:77]
	s_waitcnt lgkmcnt(2)
	v_cndmask_b32_e64 v179, v166, v167, s[36:37]
	s_waitcnt lgkmcnt(1)
	v_add_f32_e32 v166, v180, v181
	v_cndmask_b32_e64 v177, v167, v178, s[36:37]
	ds_bpermute_b32 v167, v219, v166
	s_waitcnt lgkmcnt(1)
	v_cndmask_b32_e64 v178, v176, v182, s[36:37]
	v_cndmask_b32_e64 v176, v182, v175, s[36:37]
	flat_store_dwordx4 v[164:165], v[176:179] sc1
	s_and_saveexec_b64 s[14:15], s[34:35]
	s_cbranch_execz .LBB0_442
	s_waitcnt lgkmcnt(0)
	v_add_f32_e32 v166, v166, v167
	ds_write_b32 v174, v166 offset:5648
.LBB0_442:
	s_or_b64 exec, exec, s[14:15]
	v_pk_mul_f32 v[132:133], v[2:3], v[132:133]
	v_pk_mul_f32 v[130:131], v[0:1], v[130:131]
	v_pk_mul_f32 v[136:137], v[6:7], v[136:137]
	v_pk_mul_f32 v[134:135], v[4:5], v[134:135]
	s_waitcnt lgkmcnt(0)
	v_pk_mul_f32 v[166:167], v[132:133], v[144:145]
	v_pk_mul_f32 v[176:177], v[130:131], v[142:143]
	v_pk_fma_f32 v[166:167], v[136:137], v[140:141], v[166:167] neg_lo:[0,0,1] neg_hi:[0,0,1]
	v_pk_fma_f32 v[176:177], v[134:135], v[138:139], v[176:177] neg_lo:[0,0,1] neg_hi:[0,0,1]
	v_pk_mul_f32 v[136:137], v[136:137], v[144:145]
	v_pk_mul_f32 v[134:135], v[134:135], v[142:143]
	v_pk_fma_f32 v[132:133], v[132:133], v[140:141], v[136:137]
	v_pk_fma_f32 v[130:131], v[130:131], v[138:139], v[134:135]
	v_cvt_pk_bf16_f32 v134, v176, v177
	v_cvt_pk_bf16_f32 v135, v166, v167
	s_lshl_b32 s76, s2, 1
	v_cvt_pk_bf16_f32 v130, v130, v131
	v_cvt_pk_bf16_f32 v131, v132, v133
	s_nop 0
	v_cndmask_b32_e64 v132, v135, v131, s[36:37]
	v_cndmask_b32_e64 v133, v134, v130, s[36:37]
	ds_bpermute_b32 v132, v218, v132
	ds_bpermute_b32 v136, v218, v133
	s_waitcnt lgkmcnt(0)
	v_cndmask_b32_e64 v133, v131, v132, s[36:37]
	v_cndmask_b32_e64 v131, v132, v135, s[36:37]
	v_cndmask_b32_e64 v132, v130, v136, s[36:37]
	v_cndmask_b32_e64 v130, v136, v134, s[36:37]
	flat_store_dwordx4 v[164:165], v[130:133] offset:256 sc1
	s_waitcnt lgkmcnt(0)
	s_barrier
	ds_read_b128 v[130:133], v173
	s_waitcnt lgkmcnt(0)
	v_mov_b32_e32 v134, v131
	v_mov_b32_e32 v135, v132
	v_mov_b32_e32 v131, v133
	v_pk_add_f32 v[130:131], v[134:135], v[130:131]
	s_nop 0
	v_add_f32_e32 v132, v130, v131
	v_add_u32_e32 v130, s3, v170
	v_ashrrev_i32_e32 v131, 31, v130
	v_lshlrev_b64 v[130:131], 6, v[130:131]
	v_lshl_add_u64 v[130:131], s[48:49], 0, v[130:131]
	v_lshl_add_u64 v[130:131], s[76:77], 2, v[130:131]
	v_lshl_add_u64 v[130:131], v[130:131], 0, v[96:97]
	v_add_co_u32_e32 v130, vcc, 0xff000, v130
	s_nop 1
	v_addc_co_u32_e32 v131, vcc, 0, v131, vcc
	flat_store_dword v[130:131], v132 offset:4064

; __device__ __forceinline__ unsigned cvt_pk_bf16(float lo, float hi) { unsigned r; asm volatile("v_cvt_pk_bf16_f32 %0, %1, %2" : "=v"(r) : "v"(lo), "v"(hi)); return r; }
; __device__ __forceinline__ float part8(const float* p) { const f32x4 a = *(const f32x4*)p, b = *(const f32x4*)(p + 4); return ((a[0] + a[1]) + (a[2] + a[3])) + ((b[0] + b[1]) + (b[2] + b[3])); }
;     __device__ __forceinline__ void operator()(const f32x4 (&acc)[2][2][4][2], const Unit& u, int wr, int wc, int fr, int fq, PG8_LAS float* xt) const {
;     ...
;         if (pn < 4 || pn >= 12) {
;             bf16_t* O = (pn < 4) ? U : V; const int col0 = (pn & 3) * BM + wc * 32 + 8 * fq;
; #pragma unroll
;             for (int ai = 0; ai < 2; ++ai)
; #pragma unroll
;                 for (int m = 0; m < 4; ++m) { const int row = row0 + ai * HALF + m * 16;
;                     const float rs = __builtin_amdgcn_rsqf(part8(ssq + (size_t)row * 8) * (1.0f / 2048.0f) + EPS);
;                     bf16_t* rowp = O + (size_t)row * 1024 + col0;
; #pragma unroll
;                     for (int bj = 0; bj < 2; ++bj) { const f32x4 v0 = acc[ai][bj][m][0] * rs, v1 = acc[ai][bj][m][1] * rs;
;                         u32x4 w; w.x = cvt_pk_bf16(v0[0], v0[1]); w.y = cvt_pk_bf16(v0[2], v0[3]); w.z = cvt_pk_bf16(v1[0], v1[1]); w.w = cvt_pk_bf16(v1[2], v1[3]);
;                         *(u32x4*)(rowp + bj * HALF) = w; } }
.LBB0_444:
	s_and_b64 vcc, exec, s[14:15]
	s_cbranch_vccz .LBB0_443
	v_lshlrev_b64 v[132:133], 5, v[162:163]
	v_lshl_add_u64 v[136:137], s[46:47], 0, v[132:133]
	flat_load_dwordx4 v[132:135], v[136:137]
	s_nop 0
	flat_load_dwordx4 v[136:139], v[136:137] offset:16
	s_cmp_lt_i32 s2, 4
	s_mov_b32 s3, 0x18200000
	s_cselect_b32 s3, s3, 0x1b200000
	s_add_u32 s6, s0, s3
	s_addc_u32 s7, s1, 0
	s_lshl_b32 s2, s2, 8
	s_and_b32 s2, s2, 0x300
	v_add_u32_e32 v130, s2, v171
	v_ashrrev_i32_e32 v131, 31, v130
	v_lshl_add_u64 v[130:131], v[130:131], 1, s[6:7]
	s_waitcnt vmcnt(0) lgkmcnt(0)
	v_mov_b32_e32 v140, v132
	v_mov_b32_e32 v141, v136
	v_mov_b32_e32 v136, v133
	v_pk_add_f32 v[132:133], v[140:141], v[136:137]
	v_mov_b32_e32 v136, v134
	v_mov_b32_e32 v137, v138
	v_mov_b32_e32 v138, v135
	v_pk_add_f32 v[134:135], v[136:137], v[138:139]
	s_nop 0
	v_pk_add_f32 v[132:133], v[132:133], v[134:135]
	v_lshlrev_b64 v[134:135], 11, v[162:163]
	v_add_f32_e32 v132, v132, v133
	v_fmamk_f32 v132, v132, 0x3a000000, v220
	v_rsq_f32_e32 v132, v132
	v_lshl_add_u64 v[134:135], v[130:131], 0, v[134:135]
	v_pk_mul_f32 v[128:129], v[128:129], v[132:133] op_sel_hi:[1,0]
	v_pk_mul_f32 v[126:127], v[126:127], v[132:133] op_sel_hi:[1,0]
	v_pk_mul_f32 v[136:137], v[124:125], v[132:133] op_sel_hi:[1,0]
	v_pk_mul_f32 v[124:125], v[122:123], v[132:133] op_sel_hi:[1,0]
	v_cvt_pk_bf16_f32 v122, v126, v127
	v_cvt_pk_bf16_f32 v123, v128, v129
	v_pk_mul_f32 v[120:121], v[120:121], v[132:133] op_sel_hi:[1,0]
	v_cvt_pk_bf16_f32 v124, v124, v125
	v_cvt_pk_bf16_f32 v125, v136, v137
	flat_store_dwordx4 v[134:135], v[122:125] sc1
	v_pk_mul_f32 v[118:119], v[118:119], v[132:133] op_sel_hi:[1,0]
	s_nop 0
	v_pk_mul_f32 v[122:123], v[116:117], v[132:133] op_sel_hi:[1,0]
	v_pk_mul_f32 v[116:117], v[114:115], v[132:133] op_sel_hi:[1,0]
	v_cvt_pk_bf16_f32 v114, v118, v119
	v_cvt_pk_bf16_f32 v115, v120, v121
	s_nop 0
	v_cvt_pk_bf16_f32 v116, v116, v117
	v_cvt_pk_bf16_f32 v117, v122, v123
	v_or_b32_e32 v122, 16, v162
	v_ashrrev_i32_e32 v123, 31, v122
	flat_store_dwordx4 v[134:135], v[114:117] offset:256 sc1
	s_nop 1
	v_lshlrev_b64 v[114:115], 5, v[122:123]
	v_lshl_add_u64 v[118:119], s[46:47], 0, v[114:115]
	flat_load_dwordx4 v[114:117], v[118:119]
	s_nop 0
	flat_load_dwordx4 v[118:121], v[118:119] offset:16
	s_waitcnt vmcnt(0) lgkmcnt(0)
	v_mov_b32_e32 v124, v114
	v_mov_b32_e32 v125, v118
	v_mov_b32_e32 v118, v115
	v_pk_add_f32 v[114:115], v[124:125], v[118:119]
	v_mov_b32_e32 v118, v116
	v_mov_b32_e32 v119, v120
	v_mov_b32_e32 v120, v117
	v_pk_add_f32 v[116:117], v[118:119], v[120:121]
	s_nop 0
	v_pk_add_f32 v[114:115], v[114:115], v[116:117]
	v_lshlrev_b64 v[116:117], 11, v[122:123]
	v_add_f32_e32 v114, v114, v115
	v_fmamk_f32 v114, v114, 0x3a000000, v220
	v_rsq_f32_e32 v114, v114
	v_lshl_add_u64 v[116:117], v[130:131], 0, v[116:117]
	v_pk_mul_f32 v[112:113], v[112:113], v[114:115] op_sel_hi:[1,0]
	v_pk_mul_f32 v[110:111], v[110:111], v[114:115] op_sel_hi:[1,0]
	v_pk_mul_f32 v[118:119], v[108:109], v[114:115] op_sel_hi:[1,0]
	v_pk_mul_f32 v[108:109], v[106:107], v[114:115] op_sel_hi:[1,0]
	v_cvt_pk_bf16_f32 v106, v110, v111
	v_cvt_pk_bf16_f32 v107, v112, v113
	v_pk_mul_f32 v[104:105], v[104:105], v[114:115] op_sel_hi:[1,0]
	v_cvt_pk_bf16_f32 v108, v108, v109
	v_cvt_pk_bf16_f32 v109, v118, v119
	flat_store_dwordx4 v[116:117], v[106:109] sc1
	v_pk_mul_f32 v[102:103], v[102:103], v[114:115] op_sel_hi:[1,0]
	s_nop 0
	v_pk_mul_f32 v[106:107], v[100:101], v[114:115] op_sel_hi:[1,0]
	v_pk_mul_f32 v[100:101], v[98:99], v[114:115] op_sel_hi:[1,0]
	v_cvt_pk_bf16_f32 v98, v102, v103
	v_cvt_pk_bf16_f32 v99, v104, v105
	s_nop 0
	v_cvt_pk_bf16_f32 v100, v100, v101
	v_cvt_pk_bf16_f32 v101, v106, v107
	v_or_b32_e32 v106, 32, v162
	v_ashrrev_i32_e32 v107, 31, v106
	flat_store_dwordx4 v[116:117], v[98:101] offset:256 sc1
	s_nop 1
	v_lshlrev_b64 v[98:99], 5, v[106:107]
	v_lshl_add_u64 v[102:103], s[46:47], 0, v[98:99]
	flat_load_dwordx4 v[98:101], v[102:103]
	s_nop 0
	flat_load_dwordx4 v[102:105], v[102:103] offset:16
	s_waitcnt vmcnt(0) lgkmcnt(0)
	v_mov_b32_e32 v108, v98
	v_mov_b32_e32 v109, v102
	v_mov_b32_e32 v102, v99
	v_pk_add_f32 v[98:99], v[108:109], v[102:103]
	v_mov_b32_e32 v102, v100
	v_mov_b32_e32 v103, v104
	v_mov_b32_e32 v104, v101
	v_pk_add_f32 v[100:101], v[102:103], v[104:105]
	s_nop 0
	v_pk_add_f32 v[98:99], v[98:99], v[100:101]
	v_lshlrev_b64 v[100:101], 11, v[106:107]
	v_add_f32_e32 v98, v98, v99
	v_fmamk_f32 v98, v98, 0x3a000000, v220
	v_rsq_f32_e32 v98, v98
	v_lshl_add_u64 v[100:101], v[130:131], 0, v[100:101]
	v_pk_mul_f32 v[94:95], v[94:95], v[98:99] op_sel_hi:[1,0]
	v_pk_mul_f32 v[92:93], v[92:93], v[98:99] op_sel_hi:[1,0]
	v_pk_mul_f32 v[102:103], v[90:91], v[98:99] op_sel_hi:[1,0]
	v_pk_mul_f32 v[90:91], v[88:89], v[98:99] op_sel_hi:[1,0]
	v_cvt_pk_bf16_f32 v88, v92, v93
	v_cvt_pk_bf16_f32 v89, v94, v95
	v_pk_mul_f32 v[86:87], v[86:87], v[98:99] op_sel_hi:[1,0]
	v_cvt_pk_bf16_f32 v90, v90, v91
	v_cvt_pk_bf16_f32 v91, v102, v103
	flat_store_dwordx4 v[100:101], v[88:91] sc1
	v_pk_mul_f32 v[84:85], v[84:85], v[98:99] op_sel_hi:[1,0]
	s_nop 0
	v_pk_mul_f32 v[88:89], v[82:83], v[98:99] op_sel_hi:[1,0]
	v_pk_mul_f32 v[82:83], v[80:81], v[98:99] op_sel_hi:[1,0]
	v_cvt_pk_bf16_f32 v80, v84, v85
	v_cvt_pk_bf16_f32 v81, v86, v87
	s_nop 0
	v_cvt_pk_bf16_f32 v82, v82, v83
	v_cvt_pk_bf16_f32 v83, v88, v89
	v_or_b32_e32 v88, 48, v162
	v_ashrrev_i32_e32 v89, 31, v88
	flat_store_dwordx4 v[100:101], v[80:83] offset:256 sc1
	s_nop 1
	v_lshlrev_b64 v[80:81], 5, v[88:89]
	v_lshl_add_u64 v[84:85], s[46:47], 0, v[80:81]
	flat_load_dwordx4 v[80:83], v[84:85]
	s_nop 0
	flat_load_dwordx4 v[84:87], v[84:85] offset:16
	s_waitcnt vmcnt(0) lgkmcnt(0)
; __device__ __forceinline__ unsigned cvt_pk_bf16(float lo, float hi) { unsigned r; asm volatile("v_cvt_pk_bf16_f32 %0, %1, %2" : "=v"(r) : "v"(lo), "v"(hi)); return r; }
; __device__ __forceinline__ float part8(const float* p) { const f32x4 a = *(const f32x4*)p, b = *(const f32x4*)(p + 4); return ((a[0] + a[1]) + (a[2] + a[3])) + ((b[0] + b[1]) + (b[2] + b[3])); }
;     __device__ __forceinline__ void operator()(const f32x4 (&acc)[2][2][4][2], const Unit& u, int wr, int wc, int fr, int fq, PG8_LAS float* xt) const {
;     ...
;                 for (int m = 0; m < 4; ++m) { const int row = row0 + ai * HALF + m * 16;
;                     const float rs = __builtin_amdgcn_rsqf(part8(ssq + (size_t)row * 8) * (1.0f / 2048.0f) + EPS);
;                     bf16_t* rowp = O + (size_t)row * 1024 + col0;
; #pragma unroll
;                     for (int bj = 0; bj < 2; ++bj) { const f32x4 v0 = acc[ai][bj][m][0] * rs, v1 = acc[ai][bj][m][1] * rs;
;                         u32x4 w; w.x = cvt_pk_bf16(v0[0], v0[1]); w.y = cvt_pk_bf16(v0[2], v0[3]); w.z = cvt_pk_bf16(v1[0], v1[1]); w.w = cvt_pk_bf16(v1[2], v1[3]);
;                         *(u32x4*)(rowp + bj * HALF) = w; } }
	v_mov_b32_e32 v90, v80
	v_mov_b32_e32 v91, v84
	v_mov_b32_e32 v84, v81
	v_pk_add_f32 v[80:81], v[90:91], v[84:85]
	v_mov_b32_e32 v84, v82
	v_mov_b32_e32 v85, v86
	v_mov_b32_e32 v86, v83
	v_pk_add_f32 v[82:83], v[84:85], v[86:87]
	s_nop 0
	v_pk_add_f32 v[80:81], v[80:81], v[82:83]
	v_lshlrev_b64 v[82:83], 11, v[88:89]
	v_add_f32_e32 v80, v80, v81
	v_fmamk_f32 v80, v80, 0x3a000000, v220
	v_rsq_f32_e32 v80, v80
	v_lshl_add_u64 v[82:83], v[130:131], 0, v[82:83]
	v_pk_mul_f32 v[78:79], v[78:79], v[80:81] op_sel_hi:[1,0]
	v_pk_mul_f32 v[76:77], v[76:77], v[80:81] op_sel_hi:[1,0]
	v_pk_mul_f32 v[84:85], v[74:75], v[80:81] op_sel_hi:[1,0]
	v_pk_mul_f32 v[74:75], v[72:73], v[80:81] op_sel_hi:[1,0]
	v_cvt_pk_bf16_f32 v72, v76, v77
	v_cvt_pk_bf16_f32 v73, v78, v79
	v_pk_mul_f32 v[70:71], v[70:71], v[80:81] op_sel_hi:[1,0]
	v_cvt_pk_bf16_f32 v74, v74, v75
	v_cvt_pk_bf16_f32 v75, v84, v85
	flat_store_dwordx4 v[82:83], v[72:75] sc1
	v_pk_mul_f32 v[68:69], v[68:69], v[80:81] op_sel_hi:[1,0]
	s_nop 0
	v_pk_mul_f32 v[72:73], v[66:67], v[80:81] op_sel_hi:[1,0]
	v_pk_mul_f32 v[66:67], v[64:65], v[80:81] op_sel_hi:[1,0]
	v_cvt_pk_bf16_f32 v64, v68, v69
	v_cvt_pk_bf16_f32 v65, v70, v71
	s_nop 0
	v_cvt_pk_bf16_f32 v66, v66, v67
	v_cvt_pk_bf16_f32 v67, v72, v73
	v_add_u32_e32 v72, 0x80, v162
	v_ashrrev_i32_e32 v73, 31, v72
	flat_store_dwordx4 v[82:83], v[64:67] offset:256 sc1
	s_nop 1
	v_lshlrev_b64 v[64:65], 5, v[72:73]
	v_lshl_add_u64 v[68:69], s[46:47], 0, v[64:65]
	flat_load_dwordx4 v[64:67], v[68:69]
	s_nop 0
	flat_load_dwordx4 v[68:71], v[68:69] offset:16
	s_waitcnt vmcnt(0) lgkmcnt(0)
	v_mov_b32_e32 v74, v64
	v_mov_b32_e32 v75, v68
	v_mov_b32_e32 v68, v65
	v_pk_add_f32 v[64:65], v[74:75], v[68:69]
	v_mov_b32_e32 v68, v66
	v_mov_b32_e32 v69, v70
	v_mov_b32_e32 v70, v67
	v_pk_add_f32 v[66:67], v[68:69], v[70:71]
	s_nop 0
	v_pk_add_f32 v[64:65], v[64:65], v[66:67]
	v_lshlrev_b64 v[66:67], 11, v[72:73]
	v_add_f32_e32 v64, v64, v65
	v_fmamk_f32 v64, v64, 0x3a000000, v220
	v_rsq_f32_e32 v64, v64
	v_lshl_add_u64 v[66:67], v[130:131], 0, v[66:67]
	v_pk_mul_f32 v[62:63], v[62:63], v[64:65] op_sel_hi:[1,0]
	v_pk_mul_f32 v[60:61], v[60:61], v[64:65] op_sel_hi:[1,0]
	v_pk_mul_f32 v[68:69], v[58:59], v[64:65] op_sel_hi:[1,0]
	v_pk_mul_f32 v[58:59], v[56:57], v[64:65] op_sel_hi:[1,0]
	v_cvt_pk_bf16_f32 v56, v60, v61
	v_cvt_pk_bf16_f32 v57, v62, v63
	v_pk_mul_f32 v[54:55], v[54:55], v[64:65] op_sel_hi:[1,0]
	v_cvt_pk_bf16_f32 v58, v58, v59
	v_cvt_pk_bf16_f32 v59, v68, v69
	flat_store_dwordx4 v[66:67], v[56:59] sc1
	v_pk_mul_f32 v[52:53], v[52:53], v[64:65] op_sel_hi:[1,0]
	s_nop 0
	v_pk_mul_f32 v[56:57], v[50:51], v[64:65] op_sel_hi:[1,0]
	v_pk_mul_f32 v[50:51], v[48:49], v[64:65] op_sel_hi:[1,0]
	v_cvt_pk_bf16_f32 v48, v52, v53
	v_cvt_pk_bf16_f32 v49, v54, v55
	s_nop 0
	v_cvt_pk_bf16_f32 v50, v50, v51
	v_cvt_pk_bf16_f32 v51, v56, v57
	v_add_u32_e32 v56, 0x90, v162
	v_ashrrev_i32_e32 v57, 31, v56
	flat_store_dwordx4 v[66:67], v[48:51] offset:256 sc1
	s_nop 1
	v_lshlrev_b64 v[48:49], 5, v[56:57]
	v_lshl_add_u64 v[52:53], s[46:47], 0, v[48:49]
	flat_load_dwordx4 v[48:51], v[52:53]
	s_nop 0
	flat_load_dwordx4 v[52:55], v[52:53] offset:16
	s_waitcnt vmcnt(0) lgkmcnt(0)
; __device__ __forceinline__ unsigned cvt_pk_bf16(float lo, float hi) { unsigned r; asm volatile("v_cvt_pk_bf16_f32 %0, %1, %2" : "=v"(r) : "v"(lo), "v"(hi)); return r; }
; __device__ __forceinline__ float part8(const float* p) { const f32x4 a = *(const f32x4*)p, b = *(const f32x4*)(p + 4); return ((a[0] + a[1]) + (a[2] + a[3])) + ((b[0] + b[1]) + (b[2] + b[3])); }
; #define PG8_BAR __builtin_amdgcn_s_barrier()
;     __device__ __forceinline__ void operator()(const f32x4 (&acc)[2][2][4][2], const Unit& u, int wr, int wc, int fr, int fq, PG8_LAS float* xt) const {
;     ...
;                 for (int m = 0; m < 4; ++m) { const int row = row0 + ai * HALF + m * 16;
;                     const float rs = __builtin_amdgcn_rsqf(part8(ssq + (size_t)row * 8) * (1.0f / 2048.0f) + EPS);
;                     bf16_t* rowp = O + (size_t)row * 1024 + col0;
; #pragma unroll
;                     for (int bj = 0; bj < 2; ++bj) { const f32x4 v0 = acc[ai][bj][m][0] * rs, v1 = acc[ai][bj][m][1] * rs;
;                         u32x4 w; w.x = cvt_pk_bf16(v0[0], v0[1]); w.y = cvt_pk_bf16(v0[2], v0[3]); w.z = cvt_pk_bf16(v1[0], v1[1]); w.w = cvt_pk_bf16(v1[2], v1[3]);
;                         *(u32x4*)(rowp + bj * HALF) = w; } }
; template <class Epi, class Sched, bool ALIGN_EPI, bool SP2, int KK, int LDA, int APN>
; __device__ __forceinline__ void gemm_phase(PG8_LAS unsigned char* lds, const Gemm g, const Sched& S, const Epi& E, const int wid) {
;     ...
;         if (!has_next) break;
; #pragma unroll
;         for (int a = 0; a < 2; ++a)
; #pragma unroll
;             for (int b = 0; b < 2; ++b)
; #pragma unroll
;                 for (int m = 0; m < 4; ++m)
; #pragma unroll
;                     for (int n = 0; n < 2; ++n) acc[a][b][m][n] = (f32x4){0.f, 0.f, 0.f, 0.f};
;         if constexpr (Epi::HAS_ACC_INIT) E.init_acc(acc, nxt, wr, wc, fr, fq);
;         cur = nxt; cA = nA; cB = nB; ++ui;
;         if constexpr (ALIGN_EPI) { if (wr == 1) PG8_BAR; }
;     }
	v_mov_b32_e32 v58, v48
	v_mov_b32_e32 v59, v52
	v_mov_b32_e32 v52, v49
	v_pk_add_f32 v[48:49], v[58:59], v[52:53]
	v_mov_b32_e32 v52, v50
	v_mov_b32_e32 v53, v54
	v_mov_b32_e32 v54, v51
	v_pk_add_f32 v[50:51], v[52:53], v[54:55]
	s_nop 0
	v_pk_add_f32 v[48:49], v[48:49], v[50:51]
	v_lshlrev_b64 v[50:51], 11, v[56:57]
	v_add_f32_e32 v48, v48, v49
	v_fmamk_f32 v48, v48, 0x3a000000, v220
	v_rsq_f32_e32 v48, v48
	v_lshl_add_u64 v[50:51], v[130:131], 0, v[50:51]
	v_pk_mul_f32 v[46:47], v[46:47], v[48:49] op_sel_hi:[1,0]
	v_pk_mul_f32 v[44:45], v[44:45], v[48:49] op_sel_hi:[1,0]
	v_pk_mul_f32 v[52:53], v[42:43], v[48:49] op_sel_hi:[1,0]
	v_pk_mul_f32 v[42:43], v[40:41], v[48:49] op_sel_hi:[1,0]
	v_cvt_pk_bf16_f32 v40, v44, v45
	v_cvt_pk_bf16_f32 v41, v46, v47
	v_pk_mul_f32 v[38:39], v[38:39], v[48:49] op_sel_hi:[1,0]
	v_cvt_pk_bf16_f32 v42, v42, v43
	v_cvt_pk_bf16_f32 v43, v52, v53
	flat_store_dwordx4 v[50:51], v[40:43] sc1
	v_pk_mul_f32 v[36:37], v[36:37], v[48:49] op_sel_hi:[1,0]
	s_nop 0
	v_pk_mul_f32 v[40:41], v[34:35], v[48:49] op_sel_hi:[1,0]
	v_pk_mul_f32 v[34:35], v[32:33], v[48:49] op_sel_hi:[1,0]
	v_cvt_pk_bf16_f32 v32, v36, v37
	v_cvt_pk_bf16_f32 v33, v38, v39
	s_nop 0
	v_cvt_pk_bf16_f32 v34, v34, v35
	v_cvt_pk_bf16_f32 v35, v40, v41
	v_add_u32_e32 v40, 0xa0, v162
	v_ashrrev_i32_e32 v41, 31, v40
	flat_store_dwordx4 v[50:51], v[32:35] offset:256 sc1
	s_nop 1
	v_lshlrev_b64 v[32:33], 5, v[40:41]
	v_lshl_add_u64 v[36:37], s[46:47], 0, v[32:33]
	flat_load_dwordx4 v[32:35], v[36:37]
	s_nop 0
	flat_load_dwordx4 v[36:39], v[36:37] offset:16
	s_waitcnt vmcnt(0) lgkmcnt(0)
	v_mov_b32_e32 v42, v32
	v_mov_b32_e32 v43, v36
	v_mov_b32_e32 v36, v33
	v_pk_add_f32 v[32:33], v[42:43], v[36:37]
	v_mov_b32_e32 v36, v34
	v_mov_b32_e32 v37, v38
	v_mov_b32_e32 v38, v35
	v_pk_add_f32 v[34:35], v[36:37], v[38:39]
	s_nop 0
	v_pk_add_f32 v[32:33], v[32:33], v[34:35]
	v_lshlrev_b64 v[34:35], 11, v[40:41]
	v_add_f32_e32 v32, v32, v33
	v_fmamk_f32 v32, v32, 0x3a000000, v220
	v_rsq_f32_e32 v32, v32
	v_lshl_add_u64 v[34:35], v[130:131], 0, v[34:35]
	v_pk_mul_f32 v[30:31], v[30:31], v[32:33] op_sel_hi:[1,0]
	v_pk_mul_f32 v[28:29], v[28:29], v[32:33] op_sel_hi:[1,0]
	v_pk_mul_f32 v[36:37], v[26:27], v[32:33] op_sel_hi:[1,0]
	v_pk_mul_f32 v[26:27], v[24:25], v[32:33] op_sel_hi:[1,0]
	v_cvt_pk_bf16_f32 v24, v28, v29
	v_cvt_pk_bf16_f32 v25, v30, v31
	v_pk_mul_f32 v[22:23], v[22:23], v[32:33] op_sel_hi:[1,0]
	v_cvt_pk_bf16_f32 v26, v26, v27
	v_cvt_pk_bf16_f32 v27, v36, v37
	flat_store_dwordx4 v[34:35], v[24:27] sc1
	v_pk_mul_f32 v[20:21], v[20:21], v[32:33] op_sel_hi:[1,0]
	s_nop 0
	v_pk_mul_f32 v[24:25], v[18:19], v[32:33] op_sel_hi:[1,0]
	v_pk_mul_f32 v[18:19], v[16:17], v[32:33] op_sel_hi:[1,0]
	v_cvt_pk_bf16_f32 v16, v20, v21
	v_cvt_pk_bf16_f32 v17, v22, v23
	s_nop 0
	v_cvt_pk_bf16_f32 v18, v18, v19
	v_cvt_pk_bf16_f32 v19, v24, v25
	v_add_u32_e32 v24, 0xb0, v162
	v_ashrrev_i32_e32 v25, 31, v24
	flat_store_dwordx4 v[34:35], v[16:19] offset:256 sc1
	s_nop 1
	v_lshlrev_b64 v[16:17], 5, v[24:25]
	v_lshl_add_u64 v[20:21], s[46:47], 0, v[16:17]
	flat_load_dwordx4 v[16:19], v[20:21]
	s_nop 0
	flat_load_dwordx4 v[20:23], v[20:21] offset:16
	s_waitcnt vmcnt(0) lgkmcnt(0)
	v_mov_b32_e32 v26, v16
	v_mov_b32_e32 v27, v20
	v_mov_b32_e32 v20, v17
	v_pk_add_f32 v[16:17], v[26:27], v[20:21]
	v_mov_b32_e32 v20, v18
	v_mov_b32_e32 v21, v22
	v_mov_b32_e32 v22, v19
	v_pk_add_f32 v[18:19], v[20:21], v[22:23]
	s_nop 0
	v_pk_add_f32 v[16:17], v[16:17], v[18:19]
	v_lshlrev_b64 v[18:19], 11, v[24:25]
	v_add_f32_e32 v16, v16, v17
	v_fmamk_f32 v16, v16, 0x3a000000, v220
	v_rsq_f32_e32 v16, v16
	v_lshl_add_u64 v[18:19], v[130:131], 0, v[18:19]
	v_pk_mul_f32 v[14:15], v[14:15], v[16:17] op_sel_hi:[1,0]
	v_pk_mul_f32 v[12:13], v[12:13], v[16:17] op_sel_hi:[1,0]
	v_pk_mul_f32 v[20:21], v[10:11], v[16:17] op_sel_hi:[1,0]
	v_pk_mul_f32 v[10:11], v[8:9], v[16:17] op_sel_hi:[1,0]
	v_cvt_pk_bf16_f32 v8, v12, v13
	v_cvt_pk_bf16_f32 v9, v14, v15
	v_pk_mul_f32 v[6:7], v[6:7], v[16:17] op_sel_hi:[1,0]
	v_cvt_pk_bf16_f32 v10, v10, v11
	v_cvt_pk_bf16_f32 v11, v20, v21
	flat_store_dwordx4 v[18:19], v[8:11] sc1
	v_pk_mul_f32 v[4:5], v[4:5], v[16:17] op_sel_hi:[1,0]
	s_nop 0
	v_pk_mul_f32 v[8:9], v[2:3], v[16:17] op_sel_hi:[1,0]
	v_pk_mul_f32 v[2:3], v[0:1], v[16:17] op_sel_hi:[1,0]
	v_cvt_pk_bf16_f32 v0, v4, v5
	v_cvt_pk_bf16_f32 v1, v6, v7
	s_nop 0
	v_cvt_pk_bf16_f32 v2, v2, v3
	v_cvt_pk_bf16_f32 v3, v8, v9
	flat_store_dwordx4 v[18:19], v[0:3] offset:256 sc1
	s_andn2_b64 vcc, exec, s[38:39]
	s_mov_b64 s[2:3], -1
	s_cbranch_vccnz .LBB0_398
